# barrier: the last leader does not wait for the acknowledgements of its generation atomics before leaving (on combined+final version)
# baseline (speedup 1.0000x reference)
; __device__ __forceinline__ unsigned xb_add(unsigned* p, unsigned v) { return __hip_atomic_fetch_add(p, v, __ATOMIC_RELAXED, __HIP_MEMORY_SCOPE_AGENT); }
; __device__ __forceinline__ void xcd_barrier(const XcdBarrier& b) {
;     ...
;             __builtin_amdgcn_fence(__ATOMIC_ACQUIRE, "agent");
;             xb_add(&bar[XB_XGEN(b.x)], 1u);
;             asm volatile("s_waitcnt vmcnt(0)" ::: "memory");
.LBB0_474:
	s_or_b64 exec, exec, s[4:5]
	v_readlane_b32 s4, v245, 50
	v_readlane_b32 s5, v245, 51
	s_nop 2
